# v35 + stick-breaking tile loop: 17 plain v_pk_mul_f32 replaced by scalar v_mul_f32 pairs (packed f32 VALU is slow to issue on gfx950)
# baseline (speedup 1.0000x reference)
; __device__ __forceinline__ unsigned pk2(float lo, float hi) { return pg8::cvt_pk_bf16(lo, hi); }
; __device__ __forceinline__ int crow(int r, int hi) { return (r & 3) + 8 * (r >> 2) + 4 * hi; }
; __device__ __forceinline__ void sb_mfma(const bf16_t* __restrict__ proj, bf16_t* __restrict__ mix, LAS unsigned char* ldsl) {
;     ...
;             u32x4 kf[4];
;             frag_read(kf, kimg, r32, hi);
;             f32x16 s;
; #pragma unroll
;             for (int r = 0; r < 16; ++r) s[r] = 0.f;
; #pragma unroll
;             for (int d0 = 0; d0 < 4; ++d0) s = __builtin_amdgcn_mfma_f32_32x32x16_bf16(as_bf(kf[d0]), as_bf(qf[d0]), s, 0, 0, 0);
;             const bool diag = (kb == t0);
;             float bt[16], kp1[16];
; #pragma unroll
;             for (int r = 0; r < 16; ++r) {
;                 const float z = fmaxf(s[r], -126.f);
;                 const float a = __builtin_amdgcn_exp2f(-z), rc = __builtin_amdgcn_rcpf(1.f + a);
;                 float be = rc, ke = a * rc;
;                 if (diag) { const bool valid = crow(r, hi) < r32; be = valid ? be : 0.f; ke = valid ? ke : 1.f; }
;                 bt[r] = be; kp1[r] = ke;
;             }
;             float gs[4], X[4];
; #pragma unroll
;             for (int c = 0; c < 4; ++c) { const float g4 = (kp1[4 * c] * kp1[4 * c + 1]) * (kp1[4 * c + 2] * kp1[4 * c + 3]); const HalfPair hp = half_swap(g4);
;                 gs[c] = hp.a * hp.b; X[c] = hi == 0 ? hp.b : 1.f; }
;             const float S2 = gs[3], S1 = S2 * gs[2], S0 = S1 * gs[1], total = S0 * gs[0];
;             const float SS[4] = {S0, S1, S2, 1.f};
;             float w[16];
; #pragma unroll
;             for (int c = 0; c < 4; ++c) {
;                 float run = A * SS[c] * X[c];
;                 w[4 * c + 3] = bt[4 * c + 3] * run; run *= kp1[4 * c + 3];
;                 w[4 * c + 2] = bt[4 * c + 2] * run; run *= kp1[4 * c + 2];
;                 w[4 * c + 1] = bt[4 * c + 1] * run; run *= kp1[4 * c + 1];
;                 w[4 * c + 0] = bt[4 * c + 0] * run;
;             }
;             A *= total;
;             u32x4 pb[2];
; #pragma unroll
;             for (int kk = 0; kk < 2; ++kk) { pb[kk].x = pk2(w[8 * kk], w[8 * kk + 1]); pb[kk].y = pk2(w[8 * kk + 2], w[8 * kk + 3]);
;                 pb[kk].z = pk2(w[8 * kk + 4], w[8 * kk + 5]); pb[kk].w = pk2(w[8 * kk + 6], w[8 * kk + 7]); }
;             pv_tile_tr(vimg, pb, o0, o1, r32, hi);
.LBB0_274:
	ds_read_b128 v[0:3], v107
	ds_read_b128 v[16:19], v107 offset:32
	ds_read_b128 v[20:23], v107 offset:64
	ds_read_b128 v[24:27], v107 offset:96
	s_waitcnt lgkmcnt(3)
	v_mfma_f32_32x32x16_bf16 v[0:15], v[0:3], v[48:51], 0
	s_waitcnt lgkmcnt(2)
	v_mfma_f32_32x32x16_bf16 v[0:15], v[16:19], v[52:55], v[0:15]
	s_waitcnt lgkmcnt(1)
	v_mfma_f32_32x32x16_bf16 v[0:15], v[20:23], v[56:59], v[0:15]
	s_waitcnt lgkmcnt(0)
	v_mfma_f32_32x32x16_bf16 v[0:15], v[24:27], v[60:63], v[0:15]
	s_nop 11
	v_max_f32_e64 v6, -v6, -v6
	v_min_f32_e32 v6, 0x42fc0000, v6
	v_exp_f32_e32 v6, v6
	v_max_f32_e64 v0, -v0, -v0
	v_min_f32_e32 v0, 0x42fc0000, v0
	v_exp_f32_e32 v0, v0
	v_add_f32_e32 v22, 1.0, v6
	v_rcp_f32_e32 v22, v22
	v_max_f32_e64 v1, -v1, -v1
	v_add_f32_e32 v16, 1.0, v0
	v_min_f32_e32 v1, 0x42fc0000, v1
	v_mul_f32_e32 v6, v6, v22
	v_cndmask_b32_e64 v23, 1.0, v6, s[16:17]
	v_max_f32_e64 v6, -v7, -v7
	v_min_f32_e32 v6, 0x42fc0000, v6
	v_exp_f32_e32 v6, v6
	v_rcp_f32_e32 v16, v16
	v_exp_f32_e32 v1, v1
	v_max_f32_e64 v2, -v2, -v2
	v_add_f32_e32 v7, 1.0, v6
	v_rcp_f32_e32 v7, v7
	v_mul_f32_e32 v17, v0, v16
	v_cndmask_b32_e64 v0, 0, v16, s[4:5]
	v_add_f32_e32 v16, 1.0, v1
	v_mul_f32_e32 v6, v6, v7
	v_cndmask_b32_e64 v25, 1.0, v6, s[18:19]
	v_max_f32_e64 v6, -v8, -v8
	v_min_f32_e32 v6, 0x42fc0000, v6
	v_exp_f32_e32 v6, v6
	v_cndmask_b32_e64 v24, 0, v7, s[18:19]
	v_rcp_f32_e32 v16, v16
	v_min_f32_e32 v2, 0x42fc0000, v2
	v_add_f32_e32 v7, 1.0, v6
	v_rcp_f32_e32 v7, v7
	v_exp_f32_e32 v2, v2
	v_mul_f32_e32 v18, v1, v16
	v_cndmask_b32_e64 v1, 0, v16, s[6:7]
	v_mul_f32_e32 v6, v6, v7
	v_cndmask_b32_e64 v27, 1.0, v6, s[20:21]
	v_max_f32_e64 v6, -v9, -v9
	v_min_f32_e32 v6, 0x42fc0000, v6
	v_exp_f32_e32 v6, v6
	v_cndmask_b32_e64 v26, 0, v7, s[20:21]
	v_cndmask_b32_e64 v16, 1.0, v18, s[6:7]
	v_add_f32_e32 v18, 1.0, v2
	v_add_f32_e32 v7, 1.0, v6
	v_rcp_f32_e32 v7, v7
	v_max_f32_e64 v3, -v3, -v3
	v_rcp_f32_e32 v18, v18
	v_min_f32_e32 v3, 0x42fc0000, v3
	v_mul_f32_e32 v6, v6, v7
	v_cndmask_b32_e64 v29, 1.0, v6, s[22:23]
	v_max_f32_e64 v6, -v10, -v10
	v_min_f32_e32 v6, 0x42fc0000, v6
	v_exp_f32_e32 v6, v6
	v_cndmask_b32_e64 v28, 0, v7, s[22:23]
	v_exp_f32_e32 v3, v3
	v_mul_f32_e32 v19, v2, v18
	v_add_f32_e32 v7, 1.0, v6
	v_rcp_f32_e32 v7, v7
	v_cndmask_b32_e64 v2, 0, v18, s[8:9]
	v_cndmask_b32_e64 v18, 1.0, v19, s[8:9]
	v_add_f32_e32 v19, 1.0, v3
	v_mul_f32_e32 v6, v6, v7
	v_cndmask_b32_e64 v31, 1.0, v6, s[24:25]
	v_max_f32_e64 v6, -v11, -v11
	v_min_f32_e32 v6, 0x42fc0000, v6
	v_exp_f32_e32 v6, v6
	v_cndmask_b32_e64 v30, 0, v7, s[24:25]
	v_max_f32_e64 v4, -v4, -v4
	v_rcp_f32_e32 v19, v19
	v_add_f32_e32 v7, 1.0, v6
	v_rcp_f32_e32 v7, v7
	v_min_f32_e32 v4, 0x42fc0000, v4
	v_exp_f32_e32 v4, v4
	v_mul_f32_e32 v20, v3, v19
	v_mul_f32_e32 v6, v6, v7
	v_cndmask_b32_e64 v33, 1.0, v6, s[26:27]
	v_max_f32_e64 v6, -v12, -v12
	v_min_f32_e32 v6, 0x42fc0000, v6
	v_exp_f32_e32 v6, v6
	v_cndmask_b32_e64 v32, 0, v7, s[26:27]
	v_cndmask_b32_e64 v3, 0, v19, s[10:11]
	v_cndmask_b32_e64 v19, 1.0, v20, s[10:11]
	v_add_f32_e32 v7, 1.0, v6
	v_rcp_f32_e32 v7, v7
	v_add_f32_e32 v20, 1.0, v4
	v_max_f32_e64 v5, -v5, -v5
	v_rcp_f32_e32 v20, v20
	v_mul_f32_e32 v6, v6, v7
	v_cndmask_b32_e64 v9, 1.0, v6, s[28:29]
	v_max_f32_e64 v6, -v13, -v13
	v_min_f32_e32 v6, 0x42fc0000, v6
	v_exp_f32_e32 v6, v6
	v_cndmask_b32_e64 v34, 0, v7, s[28:29]
	v_min_f32_e32 v5, 0x42fc0000, v5
	v_exp_f32_e32 v5, v5
	v_add_f32_e32 v7, 1.0, v6
	v_rcp_f32_e32 v7, v7
	v_mul_f32_e32 v21, v4, v20
	v_cndmask_b32_e64 v4, 0, v20, s[12:13]
	v_cndmask_b32_e64 v20, 1.0, v21, s[12:13]
	v_mul_f32_e32 v6, v6, v7
	v_cndmask_b32_e64 v36, 1.0, v6, s[30:31]
	v_max_f32_e64 v6, -v14, -v14
	v_min_f32_e32 v6, 0x42fc0000, v6
	v_exp_f32_e32 v6, v6
	v_cndmask_b32_e64 v35, 0, v7, s[30:31]
	v_add_f32_e32 v21, 1.0, v5
	v_rcp_f32_e32 v21, v21
	v_add_f32_e32 v7, 1.0, v6
	v_rcp_f32_e32 v7, v7
	v_cndmask_b32_e64 v17, 1.0, v17, s[4:5]
	v_mul_f32_e32 v5, v5, v21
	v_cndmask_b32_e64 v5, 1.0, v5, s[14:15]
	v_mul_f32_e32 v6, v6, v7
	v_cndmask_b32_e64 v37, 1.0, v6, s[34:35]
	v_max_f32_e64 v6, -v15, -v15
	v_min_f32_e32 v6, 0x42fc0000, v6
	v_exp_f32_e32 v6, v6
	v_cndmask_b32_e64 v14, 0, v7, s[34:35]
	v_mul_f32_e32 v10, v23, v25
	v_mul_f32_e32 v11, v31, v33
	v_add_f32_e32 v7, 1.0, v6
	v_rcp_f32_e32 v7, v7
	v_mul_f32_e32 v9, v9, v36
	v_cndmask_b32_e64 v22, 0, v22, s[16:17]
	v_cndmask_b32_e64 v21, 0, v21, s[14:15]
	v_mul_f32_e32 v6, v6, v7
	v_cndmask_b32_e64 v15, 1.0, v6, s[36:37]
	v_cndmask_b32_e64 v38, 0, v7, s[36:37]
	v_mul_f32_e32 v6, v17, v16
	v_mul_f32_e32 v7, v18, v19
	v_mul_f32_e32 v6, v6, v7
	v_mul_f32_e32 v7, v20, v5
	v_mul_f32_e32 v7, v7, v10
	v_mov_b32_e32 v10, v7
	s_nop 1
	v_permlane32_swap_b32_e32 v7, v10
	v_mul_f32_e32 v7, v7, v10
	v_cndmask_b32_e64 v20, 1.0, v10, s[0:1]
	v_mul_f32_e32 v10, v27, v29
	v_mul_f32_e32 v10, v10, v11
	v_mul_f32_e32 v11, v37, v15
	v_mul_f32_e32 v11, v9, v11
	v_mov_b32_e32 v12, v10
	v_mov_b32_e32 v13, v11
	s_nop 0
	v_permlane32_swap_b32_e32 v10, v12
	v_permlane32_swap_b32_e32 v11, v13
	v_mul_f32_e32 v10, v10, v12
	v_mul_f32_e32 v11, v11, v13
	v_mov_b32_e32 v8, v6
	v_cndmask_b32_e64 v27, 1.0, v12, s[0:1]
	v_cndmask_b32_e64 v39, 1.0, v13, s[0:1]
	v_pk_mul_f32 v[12:13], v[10:11], v[10:11] op_sel:[0,1] op_sel_hi:[1,0]
	v_permlane32_swap_b32_e32 v6, v8
	v_mov_b32_e32 v9, v12
	v_cndmask_b32_e64 v17, 1.0, v8, s[0:1]
	v_mul_f32_e32 v6, v6, v8
	v_mul_f32_e32 v7, v7, v9
	v_mul_f32_e32 v15, v39, v15
	v_mul_f32_e32 v8, v17, v7
	v_mul_f32_e32 v3, v3, v8
	v_mul_f32_e32 v8, v19, v8
	v_mul_f32_e32 v2, v2, v8
	v_mul_f32_e32 v8, v18, v8
	v_mul_f32_e32 v1, v1, v8
	v_mul_f32_e32 v8, v16, v8
	v_mul_f32_e32 v0, v0, v8
	v_mul_f32_e32 v8, v20, v12
	v_mul_f32_e32 v9, v24, v8
	v_mul_f32_e32 v8, v25, v8
	v_mul_f32_e32 v10, v22, v8
	v_mul_f32_e32 v8, v23, v8
	v_mul_f32_e32 v5, v5, v8
	v_mul_f32_e32 v4, v4, v5
	v_mul_f32_e32 v5, v27, v11
	v_mul_f32_e32 v12, v21, v8
	v_mul_f32_e32 v8, v32, v5
	v_mul_f32_e32 v5, v33, v5
	v_mul_f32_e32 v11, v30, v5
	v_mul_f32_e32 v5, v31, v5
	v_mul_f32_e32 v13, v28, v5
	v_mul_f32_e32 v5, v29, v5
	v_mul_f32_e32 v14, v14, v15
	v_mul_f32_e32 v15, v37, v15
	v_mul_f32_e32 v5, v26, v5
	v_mul_f32_e32 v17, v35, v15
	v_mul_f32_e32 v15, v36, v15
	v_mul_f32_e32 v16, v38, v39
	v_mul_f32_e32 v15, v34, v15
	v_mul_f32_e32 v101, v6, v7
	v_cvt_pk_bf16_f32 v0, v0, v1
	v_cvt_pk_bf16_f32 v1, v2, v3
	v_cvt_pk_bf16_f32 v2, v4, v12
	v_cvt_pk_bf16_f32 v3, v10, v9
	v_cvt_pk_bf16_f32 v32, v5, v13
	v_cvt_pk_bf16_f32 v33, v11, v8
	v_cvt_pk_bf16_f32 v34, v15, v17
	v_cvt_pk_bf16_f32 v35, v14, v16
	ds_read_b64_tr_b16 v[4:5], v108 offset:4608
	ds_read_b64_tr_b16 v[6:7], v108 offset:5760
	ds_read_b64_tr_b16 v[8:9], v108 offset:4672
	ds_read_b64_tr_b16 v[10:11], v108 offset:5824
	s_waitcnt lgkmcnt(2)
; #define LAS __attribute__((address_space(3)))
; __device__ __forceinline__ u32x2 tr_read(const LAS unsigned char* p) { return __builtin_bit_cast(u32x2, __builtin_amdgcn_ds_read_tr16_b64_v4i16((LAS v4i16_t*)p)); }
; __device__ __forceinline__ void pv_tile_tr(const LAS unsigned char* vimg, const u32x4 (&pb)[2], f32x16& o0, f32x16& o1, int r32, int hi) {
;     const int li = r32 & 15, dh = r32 >> 4;
;     const LAS unsigned char* base = vimg + (4 * hi + (li >> 2)) * 144 + (16 * dh + 4 * (li & 3)) * 2;
; #pragma unroll
;     for (int kk = 0; kk < 2; ++kk) {
;         const u32x2 l0 = tr_read(base + (16 * kk) * 144), h0 = tr_read(base + (16 * kk + 8) * 144);
;         const u32x2 l1 = tr_read(base + (16 * kk) * 144 + 64), h1 = tr_read(base + (16 * kk + 8) * 144 + 64);
;         const u32x4 va0 = {l0.x, l0.y, h0.x, h0.y}, va1 = {l1.x, l1.y, h1.x, h1.y};
;         o0 = __builtin_amdgcn_mfma_f32_32x32x16_bf16(as_bf(va0), as_bf(pb[kk]), o0, 0, 0, 0);
;         o1 = __builtin_amdgcn_mfma_f32_32x32x16_bf16(as_bf(va1), as_bf(pb[kk]), o1, 0, 0, 0);
;     }
; }
; __device__ __forceinline__ void sb_mfma(const bf16_t* __restrict__ proj, bf16_t* __restrict__ mix, LAS unsigned char* ldsl) {
;     ...
;             pv_tile_tr(vimg, pb, o0, o1, r32, hi);
;             if (__all(A < 1.17549435e-38f)) break;
	v_mfma_f32_32x32x16_bf16 v[16:31], v[4:7], v[0:3], 0
	ds_read_b64_tr_b16 v[36:37], v108 offset:6912
	ds_read_b64_tr_b16 v[38:39], v108 offset:8064
	ds_read_b64_tr_b16 v[40:41], v108 offset:6976
	ds_read_b64_tr_b16 v[42:43], v108 offset:8128
	v_cmp_gt_f32_e32 vcc, s3, v101
	s_cmp_eq_u64 vcc, exec
	s_cselect_b64 s[48:49], -1, 0
	s_cmp_eq_u32 s45, 0
	s_cselect_b64 s[50:51], -1, 0
	s_or_b64 s[48:49], s[50:51], s[48:49]
	s_waitcnt lgkmcnt(4)
	v_mfma_f32_32x32x16_bf16 v[0:15], v[8:11], v[0:3], 0
	s_and_b64 vcc, exec, s[48:49]
	s_mov_b32 s48, s45
	s_waitcnt lgkmcnt(2)
	v_mfma_f32_32x32x16_bf16 v[16:31], v[36:39], v[32:35], v[16:31]
	s_waitcnt lgkmcnt(0)
	v_mfma_f32_32x32x16_bf16 v[0:15], v[40:43], v[32:35], v[0:15]
	s_cbranch_vccz .LBB0_276
	s_branch .LBB0_271
; __device__ __forceinline__ unsigned pk2(float lo, float hi) { return pg8::cvt_pk_bf16(lo, hi); }
; __device__ __forceinline__ void sb_mfma(const bf16_t* __restrict__ proj, bf16_t* __restrict__ mix, LAS unsigned char* ldsl) {
;     ...
;             frag_read(kf, kimg, r32, hi);
;             f32x16 s;
; #pragma unroll
;             for (int r = 0; r < 16; ++r) s[r] = 0.f;
; #pragma unroll
;             for (int d0 = 0; d0 < 4; ++d0) s = __builtin_amdgcn_mfma_f32_32x32x16_bf16(as_bf(kf[d0]), as_bf(qf[d0]), s, 0, 0, 0);
;             const bool diag = (kb == t0);
;             float bt[16], kp1[16];
; #pragma unroll
;             for (int r = 0; r < 16; ++r) {
;                 const float z = fmaxf(s[r], -126.f);
;                 const float a = __builtin_amdgcn_exp2f(-z), rc = __builtin_amdgcn_rcpf(1.f + a);
;                 float be = rc, ke = a * rc;
;                 if (diag) { const bool valid = crow(r, hi) < r32; be = valid ? be : 0.f; ke = valid ? ke : 1.f; }
;                 bt[r] = be; kp1[r] = ke;
;             }
;             float gs[4], X[4];
; #pragma unroll
;             for (int c = 0; c < 4; ++c) { const float g4 = (kp1[4 * c] * kp1[4 * c + 1]) * (kp1[4 * c + 2] * kp1[4 * c + 3]); const HalfPair hp = half_swap(g4);
;                 gs[c] = hp.a * hp.b; X[c] = hi == 0 ? hp.b : 1.f; }
;             const float S2 = gs[3], S1 = S2 * gs[2], S0 = S1 * gs[1], total = S0 * gs[0];
;             const float SS[4] = {S0, S1, S2, 1.f};
;             float w[16];
; #pragma unroll
;             for (int c = 0; c < 4; ++c) {
;                 float run = A * SS[c] * X[c];
;                 w[4 * c + 3] = bt[4 * c + 3] * run; run *= kp1[4 * c + 3];
;                 w[4 * c + 2] = bt[4 * c + 2] * run; run *= kp1[4 * c + 2];
;                 w[4 * c + 1] = bt[4 * c + 1] * run; run *= kp1[4 * c + 1];
;                 w[4 * c + 0] = bt[4 * c + 0] * run;
;             }
;             A *= total;
;             u32x4 pb[2];
; #pragma unroll
;             for (int kk = 0; kk < 2; ++kk) { pb[kk].x = pk2(w[8 * kk], w[8 * kk + 1]); pb[kk].y = pk2(w[8 * kk + 2], w[8 * kk + 3]);
;                 pb[kk].z = pk2(w[8 * kk + 4], w[8 * kk + 5]); pb[kk].w = pk2(w[8 * kk + 6], w[8 * kk + 7]); }
;             pv_tile_tr(vimg, pb, o0, o1, r32, hi);
;             if (__all(A < 1.17549435e-38f)) break;
.LBB0_275:
	s_waitcnt lgkmcnt(7)
	v_mfma_f32_32x32x16_bf16 v[32:47], v[118:121], v[48:51], 0
	s_waitcnt lgkmcnt(6)
	v_mfma_f32_32x32x16_bf16 v[32:47], v[110:113], v[52:55], v[32:47]
	s_waitcnt lgkmcnt(5)
	v_mfma_f32_32x32x16_bf16 v[32:47], v[122:125], v[56:59], v[32:47]
	s_waitcnt lgkmcnt(4)
	v_mfma_f32_32x32x16_bf16 v[32:47], v[114:117], v[60:63], v[32:47]
	s_nop 11
	v_max_f32_e64 v44, -v44, -v44
	v_max_f32_e64 v32, -v32, -v32
	v_max_f32_e64 v37, -v37, -v37
	v_max_f32_e64 v38, -v38, -v38
	v_min_f32_e32 v44, 0x42fc0000, v44
	v_max_f32_e64 v39, -v39, -v39
	v_min_f32_e32 v32, 0x42fc0000, v32
	v_min_f32_e32 v37, 0x42fc0000, v37
	v_min_f32_e32 v105, 0x42fc0000, v38
	v_exp_f32_e32 v44, v44
	v_min_f32_e32 v39, 0x42fc0000, v39
	v_exp_f32_e32 v32, v32
	v_exp_f32_e32 v38, v37
	v_exp_f32_e32 v37, v105
	v_exp_f32_e32 v39, v39
	v_max_f32_e64 v45, -v45, -v45
	v_max_f32_e64 v33, -v33, -v33
	v_min_f32_e32 v45, 0x42fc0000, v45
	v_max_f32_e64 v34, -v34, -v34
	v_max_f32_e64 v40, -v40, -v40
	v_min_f32_e32 v33, 0x42fc0000, v33
	v_exp_f32_e32 v122, v45
	v_add_f32_e32 v45, 1.0, v44
	v_min_f32_e32 v103, 0x42fc0000, v34
	v_min_f32_e32 v109, 0x42fc0000, v40
	v_exp_f32_e32 v34, v33
	v_add_f32_e32 v40, 1.0, v32
	v_add_f32_e32 v115, 1.0, v38
	v_add_f32_e32 v116, 1.0, v37
	v_max_f32_e64 v41, -v41, -v41
	v_max_f32_e64 v42, -v42, -v42
	v_rcp_f32_e32 v124, v45
	v_max_f32_e64 v45, -v46, -v46
	v_add_f32_e32 v117, 1.0, v39
	v_rcp_f32_e32 v110, v40
	v_rcp_f32_e32 v40, v115
	v_rcp_f32_e32 v115, v116
	v_exp_f32_e32 v116, v109
	v_min_f32_e32 v41, 0x42fc0000, v41
	v_min_f32_e32 v42, 0x42fc0000, v42
	v_min_f32_e32 v45, 0x42fc0000, v45
	v_max_f32_e64 v46, -v47, -v47
	v_exp_f32_e32 v118, v41
	v_rcp_f32_e32 v41, v117
	v_exp_f32_e32 v117, v42
	v_max_f32_e64 v42, -v43, -v43
	v_exp_f32_e32 v45, v45
	v_min_f32_e32 v46, 0x42fc0000, v46
	v_min_f32_e32 v42, 0x42fc0000, v42
	v_exp_f32_e32 v123, v46
	v_max_f32_e64 v36, -v36, -v36
	v_exp_f32_e32 v33, v103
	v_add_f32_e32 v103, 1.0, v34
	v_exp_f32_e32 v119, v42
	v_min_f32_e32 v36, 0x42fc0000, v36
	v_rcp_f32_e32 v112, v103
	v_add_f32_e32 v103, 1.0, v116
	v_max_f32_e64 v35, -v35, -v35
	v_exp_f32_e32 v36, v36
	v_rcp_f32_e32 v120, v103
	v_add_f32_e32 v103, 1.0, v118
	v_add_f32_e32 v47, 1.0, v45
	v_min_f32_e32 v35, 0x42fc0000, v35
	v_rcp_f32_e32 v42, v103
	v_add_f32_e32 v43, 1.0, v117
	v_add_f32_e32 v103, 1.0, v122
	v_rcp_f32_e32 v125, v47
	v_add_f32_e32 v47, 1.0, v123
	v_exp_f32_e32 v35, v35
	v_rcp_f32_e32 v121, v43
	v_add_f32_e32 v43, 1.0, v119
	v_rcp_f32_e32 v46, v103
	v_rcp_f32_e32 v47, v47
	v_rcp_f32_e32 v43, v43
	v_add_f32_e32 v114, 1.0, v36
	v_rcp_f32_e32 v114, v114
	v_add_f32_e32 v105, 1.0, v33
	v_add_f32_e32 v113, 1.0, v35
	v_mul_f32_e32 v44, v44, v124
	v_mul_f32_e32 v45, v45, v125
	v_mul_f32_e32 v122, v122, v46
	v_mul_f32_e32 v123, v123, v47
	v_rcp_f32_e32 v111, v105
	v_rcp_f32_e32 v113, v113
	v_mul_f32_e32 v116, v116, v120
	v_mul_f32_e32 v117, v117, v121
	v_mul_f32_e32 v118, v118, v42
	v_mul_f32_e32 v119, v119, v43
	v_mul_f32_e32 v138, v44, v122
	v_mul_f32_e32 v139, v45, v123
	v_mul_f32_e32 v134, v116, v118
	v_mul_f32_e32 v135, v117, v119
	v_pk_mul_f32 v[138:139], v[138:139], v[138:139] op_sel:[0,1] op_sel_hi:[1,0]
	v_mul_f32_e32 v36, v36, v114
	v_mul_f32_e32 v37, v37, v115
	v_mul_f32_e32 v38, v38, v40
	v_mul_f32_e32 v39, v39, v41
	v_pk_mul_f32 v[134:135], v[134:135], v[134:135] op_sel:[0,1] op_sel_hi:[1,0]
	v_mov_b32_e32 v137, v138
	v_mul_f32_e32 v130, v36, v38
	v_mul_f32_e32 v131, v37, v39
	v_mov_b32_e32 v136, v134
	v_permlane32_swap_b32_e32 v138, v137
	v_mul_f32_e32 v32, v32, v110
	v_mul_f32_e32 v33, v33, v111
	v_mul_f32_e32 v34, v34, v112
	v_mul_f32_e32 v35, v35, v113
	v_pk_mul_f32 v[130:131], v[130:131], v[130:131] op_sel:[0,1] op_sel_hi:[1,0]
	v_permlane32_swap_b32_e32 v134, v136
	v_mov_b32_e32 v135, v138
	v_mul_f32_e32 v126, v32, v34
	v_mul_f32_e32 v127, v33, v35
	v_mov_b32_e32 v132, v130
	v_mul_f32_e32 v134, v134, v136
	v_mul_f32_e32 v135, v135, v137
	v_pk_mul_f32 v[126:127], v[126:127], v[126:127] op_sel:[0,1] op_sel_hi:[1,0]
	v_permlane32_swap_b32_e32 v130, v132
	v_mov_b32_e32 v131, v134
	v_mov_b32_e32 v133, v135
	v_mov_b32_e32 v128, v126
	v_mul_f32_e32 v130, v130, v132
	v_mul_f32_e32 v131, v131, v133
	s_nop 0
	v_permlane32_swap_b32_e32 v126, v128
	v_mov_b32_e32 v127, v130
	v_mov_b32_e32 v129, v131
	v_mul_f32_e32 v126, v126, v128
	v_mul_f32_e32 v127, v127, v129
	v_cndmask_b32_e64 v32, 1.0, v128, s[0:1]
	v_mul_f32_e32 v105, v101, v127
	v_mul_f32_e32 v32, v32, v105
	v_mul_f32_e32 v105, v113, v32
	v_mul_f32_e32 v32, v35, v32
	v_mul_f32_e32 v35, v111, v32
	v_mul_f32_e32 v32, v33, v32
	v_cndmask_b32_e64 v36, 1.0, v132, s[0:1]
	v_mul_f32_e32 v33, v112, v32
	v_mul_f32_e32 v32, v34, v32
	v_mul_f32_e32 v34, v101, v131
	v_mul_f32_e32 v34, v36, v34
	v_mul_f32_e32 v36, v41, v34
	v_mul_f32_e32 v34, v39, v34
	v_mul_f32_e32 v39, v115, v34
	v_mul_f32_e32 v34, v37, v34
	v_cndmask_b32_e64 v44, 1.0, v136, s[0:1]
	v_mul_f32_e32 v37, v40, v34
	v_mul_f32_e32 v34, v38, v34
	v_mul_f32_e32 v38, v101, v135
	v_cndmask_b32_e64 v103, 1.0, v137, s[0:1]
	v_mul_f32_e32 v38, v44, v38
	v_mul_f32_e32 v40, v43, v38
	v_mul_f32_e32 v43, v101, v103
	v_mul_f32_e32 v38, v119, v38
	v_mul_f32_e32 v44, v47, v43
	v_mul_f32_e32 v43, v123, v43
	v_mul_f32_e32 v41, v121, v38
	v_mul_f32_e32 v38, v117, v38
	v_mul_f32_e32 v47, v125, v43
	v_mul_f32_e32 v43, v45, v43
	v_mul_f32_e32 v42, v42, v38
	v_mul_f32_e32 v38, v118, v38
	v_mul_f32_e32 v45, v46, v43
	v_mul_f32_e32 v43, v122, v43
	v_mul_f32_e32 v32, v110, v32
	v_mul_f32_e32 v34, v114, v34
	v_mul_f32_e32 v38, v120, v38
	v_mul_f32_e32 v43, v124, v43
	v_cvt_pk_bf16_f32 v32, v32, v33
	v_cvt_pk_bf16_f32 v33, v35, v105
	v_cvt_pk_bf16_f32 v34, v34, v37
	v_cvt_pk_bf16_f32 v35, v39, v36
	v_cvt_pk_bf16_f32 v36, v38, v42
	v_cvt_pk_bf16_f32 v37, v41, v40
	v_cvt_pk_bf16_f32 v38, v43, v45
	v_cvt_pk_bf16_f32 v39, v47, v44
	ds_read_b64_tr_b16 v[40:41], v108 offset:4608
	ds_read_b64_tr_b16 v[42:43], v108 offset:5760
	ds_read_b64_tr_b16 v[46:47], v108 offset:5824
	ds_read_b64_tr_b16 v[44:45], v108 offset:4672
	s_waitcnt lgkmcnt(2)
	v_mfma_f32_32x32x16_bf16 v[16:31], v[40:43], v[32:35], v[16:31]
	s_waitcnt lgkmcnt(0)
	v_mfma_f32_32x32x16_bf16 v[0:15], v[44:47], v[32:35], v[0:15]
	ds_read_b64_tr_b16 v[32:33], v108 offset:6912
	ds_read_b64_tr_b16 v[34:35], v108 offset:8064
	ds_read_b64_tr_b16 v[42:43], v108 offset:8128
	ds_read_b64_tr_b16 v[40:41], v108 offset:6976
	s_waitcnt lgkmcnt(2)
	v_mfma_f32_32x32x16_bf16 v[16:31], v[32:35], v[36:39], v[16:31]
	v_mul_f32_e32 v32, v126, v127
	v_mul_f32_e32 v101, v101, v32
	v_cmp_gt_f32_e32 vcc, s3, v101
	s_cmp_lg_u64 vcc, exec
	s_cselect_b64 s[50:51], -1, 0
	s_cmp_gt_u32 s48, 63
	s_cselect_b64 s[66:67], -1, 0
	s_waitcnt lgkmcnt(0)
	v_mfma_f32_32x32x16_bf16 v[0:15], v[40:43], v[36:39], v[0:15]
	s_and_b64 s[50:51], s[66:67], s[50:51]
	s_sub_i32 s48, s48, 32
	s_and_b64 vcc, exec, s[50:51]
	s_cbranch_vccz .LBB0_271
